# mixer work queue: the next-unit dequeue atomic is issued at unit start without waiting; its result is picked up (scalar decode) at the next loop head, so the dequeue round trip overlaps the unit
# speedup vs baseline: 1.0775x; 1.0045x over previous
.LBB0_848:
	s_or_b64 exec, exec, s[0:1]
	s_mov_b32 s58, 0
	v_writelane_b32 v255, s58, 44
	s_lshl_b32 s96, s74, 6
	s_lshl_b64 s[0:1], s[96:97], 2
	s_add_u32 s70, s40, s0
	s_addc_u32 s71, s41, s1
	s_lshl_b32 s96, s74, 9
	s_lshl_b64 s[0:1], s[96:97], 2
	v_readlane_b32 s4, v254, 29
	s_add_u32 s82, s4, s0
	v_readlane_b32 s0, v254, 30
	s_addc_u32 s83, s0, s1
	v_mov_b32_e32 v197, 0x7d0
	s_mov_b64 s[84:85], 0
	v_mov_b32_e32 v196, 0
	s_waitcnt lgkmcnt(0)
	s_barrier
	s_and_saveexec_b64 s[0:1], s[26:27]
	s_cbranch_execz .LBB0_900
	s_mov_b64 s[6:7], exec
	v_mbcnt_lo_u32_b32 v0, s6, 0
	v_mbcnt_hi_u32_b32 v0, s7, v0
	v_cmp_eq_u32_e32 vcc, 0, v0
	s_and_saveexec_b64 s[4:5], vcc
	s_cbranch_execz .LBB0_851
	s_bcnt1_i32_b64 s6, s[6:7]
	v_mov_b32_e32 v1, s6
	global_atomic_add v1, v65, v1, s[70:71] offset:256 sc0

.LBB0_903:
	s_barrier
	s_and_saveexec_b64 s[0:1], s[26:27]
	s_cbranch_execz .Lclaim_fin_done
	v_readlane_b32 s58, v255, 44
	s_cmp_eq_u32 s58, 0
	s_cbranch_scc1 .Lclaim_fin_done
	s_mov_b32 s58, 0
	v_writelane_b32 v255, s58, 44
	v_readfirstlane_b32 s58, v197
	v_readfirstlane_b32 s59, v196
	s_cmp_lg_u32 s58, -1
	s_cbranch_scc1 .Lclaim_fin_loop
	s_waitcnt vmcnt(0)
	s_nop 0
	v_readfirstlane_b32 s58, v197
.Lclaim_fin_loop:
	s_add_i32 s60, s59, s3
	s_and_b32 s60, s60, 7
	s_cmpk_gt_u32 s58, 0xf7
	s_cbranch_scc1 .Lclaim_fin_next
	s_cmpk_lt_u32 s58, 0x8
	s_cbranch_scc1 .Lclaim_seg0
	s_cmpk_lt_u32 s58, 0x28
	s_cbranch_scc1 .Lclaim_seg1
	s_cmpk_lt_u32 s58, 0x48
	s_cbranch_scc1 .Lclaim_seg2
	s_cmpk_lt_u32 s58, 0x68
	s_cbranch_scc1 .Lclaim_seg3
	s_cmpk_lt_u32 s58, 0x78
	s_cbranch_scc1 .Lclaim_seg4
	s_cmpk_lt_u32 s58, 0x98
	s_cbranch_scc1 .Lclaim_seg5
	s_cmpk_lt_u32 s58, 0xa8
	s_cbranch_scc1 .Lclaim_seg6
	s_cmpk_lt_u32 s58, 0xb8
	s_cbranch_scc1 .Lclaim_seg7
	s_cmpk_lt_u32 s58, 0xc8
	s_cbranch_scc1 .Lclaim_seg8
	s_cmpk_lt_u32 s58, 0xe8
	s_cbranch_scc1 .Lclaim_seg9
	s_cmpk_lt_u32 s58, 0xf8
	s_cbranch_scc1 .Lclaim_seg10
	s_branch .Lclaim_fin_next
.Lclaim_seg0:
	s_lshl_b32 s61, s60, 3
	s_add_i32 s61, s61, s58
	s_add_i32 s61, s61, 0x590
	s_branch .Lclaim_fin_set
.Lclaim_seg1:
	s_lshl_b32 s61, s60, 5
	s_add_i32 s61, s61, s58
	s_add_i32 s61, s61, 0x188
	s_branch .Lclaim_fin_set
.Lclaim_seg2:
	s_lshl_b32 s61, s60, 5
	s_add_i32 s61, s61, s58
	s_add_i32 s61, s61, 0x268
	s_branch .Lclaim_fin_set
.Lclaim_seg3:
	s_lshl_b32 s61, s60, 5
	s_add_i32 s61, s61, s58
	s_sub_i32 s61, s61, 0x38
	s_branch .Lclaim_fin_set
.Lclaim_seg4:
	s_lshl_b32 s61, s60, 4
	s_add_i32 s61, s61, s58
	s_add_i32 s61, s61, 0xa8
	s_branch .Lclaim_fin_set
.Lclaim_seg5:
	s_lshl_b32 s61, s60, 5
	s_add_i32 s61, s61, s58
	s_add_i32 s61, s61, 0x318
	s_branch .Lclaim_fin_set
.Lclaim_seg6:
	s_lshl_b32 s61, s60, 4
	s_add_i32 s61, s61, s58
	s_add_i32 s61, s61, 0x3f8
	s_branch .Lclaim_fin_set
.Lclaim_seg7:
	s_lshl_b32 s61, s60, 4
	s_add_i32 s61, s61, s58
	s_add_i32 s61, s61, 0x468
	s_branch .Lclaim_fin_set
.Lclaim_seg8:
	s_lshl_b32 s61, s60, 4
	s_add_i32 s61, s61, s58
	s_add_i32 s61, s61, 0x698
	s_branch .Lclaim_fin_set
.Lclaim_seg9:
	s_lshl_b32 s61, s60, 5
	s_add_i32 s61, s61, s58
	s_add_i32 s61, s61, 0x508
	s_branch .Lclaim_fin_set
.Lclaim_seg10:
	s_lshl_b32 s61, s60, 4
	s_add_i32 s61, s61, s58
	s_add_i32 s61, s61, 0x5e8
	s_branch .Lclaim_fin_set
.Lclaim_fin_next:
	s_add_i32 s59, s59, 1
	s_cmp_gt_i32 s59, 7
	s_cbranch_scc1 .Lclaim_fin_end
	s_add_i32 s60, s59, s3
	s_and_b32 s60, s60, 7
	s_lshl_b32 s61, s60, 8
	v_mov_b32_e32 v0, s61
	s_nop 1
	global_atomic_add v0, v0, v230, s[82:83] sc0
	s_waitcnt vmcnt(0)
	s_nop 0
	v_readfirstlane_b32 s58, v0
	s_branch .Lclaim_fin_loop
.Lclaim_fin_end:
	s_movk_i32 s61, 0x7d0
.Lclaim_fin_set:
	v_mov_b32_e32 v197, s61
	v_mov_b32_e32 v196, s59
.Lclaim_fin_done:
	v_mov_b32_e32 v0, s47
	ds_write_b32 v0, v197
	s_or_b64 exec, exec, s[0:1]
	v_mov_b32_e32 v0, s47
	s_waitcnt lgkmcnt(0)
	s_barrier
	ds_read_b32 v0, v0
	s_movk_i32 s0, 0x7cf
	s_waitcnt lgkmcnt(0)
	v_cmp_lt_i32_e64 s[4:5], s0, v0
	v_readfirstlane_b32 s86, v0
	s_and_b64 vcc, exec, s[4:5]
	s_cbranch_vccnz .LBB0_902
	s_and_saveexec_b64 s[0:1], s[26:27]
	s_cbranch_execz .LBB0_960
	s_and_b64 vcc, exec, s[84:85]
	s_cbranch_vccz .Lclaim_sync
	v_readfirstlane_b32 s58, v196
	s_cmp_gt_i32 s58, 7
	s_cbranch_scc1 .Lclaim_none
	s_add_i32 s58, s58, s3
	s_and_b32 s58, s58, 7
	s_lshl_b32 s58, s58, 8
	v_mov_b32_e32 v0, s58
	s_mov_b32 s59, 1
	v_writelane_b32 v255, s59, 44
	v_mov_b32_e32 v197, -1
	s_nop 1
	global_atomic_add v197, v0, v230, s[82:83] sc0
	s_branch .LBB0_960
.Lclaim_none:
	v_mov_b32_e32 v197, 0x7d0
	s_branch .LBB0_960
.Lclaim_sync:
	s_xor_b64 s[10:11], s[84:85], -1
	v_mov_b32_e32 v197, 0x7d0
	s_mov_b64 s[8:9], -1
	s_and_saveexec_b64 s[6:7], s[10:11]
	s_cbranch_execz .LBB0_911
	s_mov_b64 s[10:11], exec
	v_mbcnt_lo_u32_b32 v0, s10, 0
	v_mbcnt_hi_u32_b32 v0, s11, v0
	v_cmp_eq_u32_e32 vcc, 0, v0
	s_and_saveexec_b64 s[8:9], vcc
	s_cbranch_execz .LBB0_910
	s_bcnt1_i32_b64 s10, s[10:11]
	v_mov_b32_e32 v1, s10
	global_atomic_add v1, v65, v1, s[70:71] offset:256 sc0
